# final RMSNorm loop: two iterations' loads in flight per thread, g kept in registers
# baseline (speedup 1.0000x reference)
; DI int ltid(int wv) { asm volatile("" : "+s"(wv)); int l = __builtin_amdgcn_mbcnt_hi(~0u, __builtin_amdgcn_mbcnt_lo(~0u, 0u)); asm volatile("" : "+v"(l)); return wv * 64 + l; }
; DI float bflo(unsigned u) { return __uint_as_float(u << 16); }
; DI float bfhi(unsigned u) { return __uint_as_float(u & 0xffff0000u); }
; DI float rs_from_ss(u64 ssq) { return rsqrtf((float)ssq * (1.f / (1048576.f * 1024.f)) + EPS); }
; DI void phase_final(int wv, const ArgP a) {
;     float* out = a.out(); const u64* rowss = (const u64*)(a.ws() + O_ROWSS) + 4 * S; const float* g = a.in(27); const bf16_t* XBr = (const bf16_t*)(a.ws() + O_XB) + 2 * 1024;
;     for (size_t e = (size_t)blockIdx.x * 512 + ltid(wv); e < (size_t)S * 128; e += (size_t)gridDim.x * 512) { const int t = (int)(e >> 7), c = (int)(e & 127) * 8;
;         const float rs = rs_from_ss(rowss[t]); const u32x4 hb = __builtin_nontemporal_load((const u32x4*)(XBr + (size_t)t * 1024 + c)); const f32x4 g0 = *(const f32x4*)(g + c), g1 = *(const f32x4*)(g + c + 4);
;         const f32x4 v0 = (f32x4){bflo(hb.x), bfhi(hb.x), bflo(hb.y), bfhi(hb.y)} * rs * g0, v1 = (f32x4){bflo(hb.z), bfhi(hb.z), bflo(hb.w), bfhi(hb.w)} * rs * g1;
;         __builtin_nontemporal_store(v0, (f32x4*)(out + (size_t)t * 1024 + c)); __builtin_nontemporal_store(v1, (f32x4*)(out + (size_t)t * 1024 + c + 4)); }
.Lfin_loop:
	v_mov_b32_e32 v30, v0
	v_mov_b32_e32 v31, v1
	v_lshl_add_u64 v[32:33], v[30:31], 0, s[8:9]
	v_cmp_gt_u64_e64 s[20:21], s[30:31], v[30:31]
	v_lshrrev_b64 v[40:41], 7, v[30:31]
	v_cmp_gt_u64_e64 s[22:23], s[30:31], v[32:33]
	v_lshrrev_b64 v[42:43], 7, v[32:33]
	v_lshl_add_u64 v[100:101], v[40:41], 3, s[0:1]
	global_load_dwordx2 v[64:65], v[100:101], off
	v_lshlrev_b64 v[100:101], 11, v[40:41]
	v_lshl_add_u64 v[100:101], s[2:3], 0, v[100:101]
	v_add_co_u32_e32 v100, vcc, v100, v60
	s_nop 1
	v_addc_co_u32_e32 v101, vcc, 0, v101, vcc
	global_load_dwordx4 v[72:75], v[100:101], off nt
	v_lshlrev_b64 v[90:91], 12, v[40:41]
	v_lshl_add_u64 v[90:91], s[6:7], 0, v[90:91]
	v_add_co_u32_e32 v90, vcc, v90, v61
	s_nop 1
	v_addc_co_u32_e32 v91, vcc, 0, v91, vcc
	v_lshl_add_u64 v[100:101], v[42:43], 3, s[0:1]
	global_load_dwordx2 v[66:67], v[100:101], off
	v_lshlrev_b64 v[100:101], 11, v[42:43]
	v_lshl_add_u64 v[100:101], s[2:3], 0, v[100:101]
	v_add_co_u32_e32 v100, vcc, v100, v60
	s_nop 1
	v_addc_co_u32_e32 v101, vcc, 0, v101, vcc
	global_load_dwordx4 v[76:79], v[100:101], off nt
	v_lshlrev_b64 v[92:93], 12, v[42:43]
	v_lshl_add_u64 v[92:93], s[6:7], 0, v[92:93]
	v_add_co_u32_e32 v92, vcc, v92, v61
	s_nop 1
	v_addc_co_u32_e32 v93, vcc, 0, v93, vcc
	v_lshl_add_u64 v[0:1], v[32:33], 0, s[8:9]
	v_cmp_lt_u64_e32 vcc, s[14:15], v[0:1]
	s_or_b64 s[12:13], vcc, s[12:13]
	s_waitcnt vmcnt(2)
	v_ffbh_u32_e32 v4, v65
	v_min_u32_e32 v4, 32, v4
	v_lshlrev_b64 v[64:65], v4, v[64:65]
	v_min_u32_e32 v7, 1, v64
	v_or_b32_e32 v7, v65, v7
	v_cvt_f32_u32_e32 v7, v7
	v_sub_u32_e32 v4, 32, v4
	v_ldexp_f32 v4, v7, v4
	v_fmamk_f32 v4, v4, 0x30800000, v6
	v_mul_f32_e32 v7, 0x4b800000, v4
	v_cmp_gt_f32_e32 vcc, s16, v4
	s_nop 1
	v_cndmask_b32_e32 v4, v4, v7, vcc
	v_rsq_f32_e32 v4, v4
	s_nop 0
	v_mul_f32_e32 v7, 0x45800000, v4
	v_cndmask_b32_e32 v4, v4, v7, vcc
	v_lshlrev_b32_e32 v104, 16, v72
	v_and_b32_e32 v105, 0xffff0000, v72
	v_lshlrev_b32_e32 v106, 16, v73
	v_and_b32_e32 v107, 0xffff0000, v73
	v_lshlrev_b32_e32 v108, 16, v74
	v_and_b32_e32 v109, 0xffff0000, v74
	v_lshlrev_b32_e32 v110, 16, v75
	v_and_b32_e32 v111, 0xffff0000, v75
	v_pk_mul_f32 v[104:105], v[4:5], v[104:105] op_sel_hi:[0,1]
	v_pk_mul_f32 v[106:107], v[4:5], v[106:107] op_sel_hi:[0,1]
	v_pk_mul_f32 v[108:109], v[4:5], v[108:109] op_sel_hi:[0,1]
	v_pk_mul_f32 v[110:111], v[4:5], v[110:111] op_sel_hi:[0,1]
	v_pk_mul_f32 v[104:105], v[12:13], v[104:105]
	v_pk_mul_f32 v[106:107], v[14:15], v[106:107]
	v_pk_mul_f32 v[108:109], v[16:17], v[108:109]
	v_pk_mul_f32 v[110:111], v[18:19], v[110:111]
	s_waitcnt vmcnt(0)
	v_ffbh_u32_e32 v4, v67
	v_min_u32_e32 v4, 32, v4
	v_lshlrev_b64 v[66:67], v4, v[66:67]
	v_min_u32_e32 v7, 1, v66
	v_or_b32_e32 v7, v67, v7
	v_cvt_f32_u32_e32 v7, v7
	v_sub_u32_e32 v4, 32, v4
	v_ldexp_f32 v4, v7, v4
	v_fmamk_f32 v4, v4, 0x30800000, v6
	v_mul_f32_e32 v7, 0x4b800000, v4
	v_cmp_gt_f32_e32 vcc, s16, v4
	s_nop 1
	v_cndmask_b32_e32 v4, v4, v7, vcc
	v_rsq_f32_e32 v4, v4
	s_nop 0
	v_mul_f32_e32 v7, 0x45800000, v4
	v_cndmask_b32_e32 v4, v4, v7, vcc
	v_lshlrev_b32_e32 v112, 16, v76
	v_and_b32_e32 v113, 0xffff0000, v76
	v_lshlrev_b32_e32 v114, 16, v77
	v_and_b32_e32 v115, 0xffff0000, v77
	v_lshlrev_b32_e32 v116, 16, v78
	v_and_b32_e32 v117, 0xffff0000, v78
	v_lshlrev_b32_e32 v118, 16, v79
	v_and_b32_e32 v119, 0xffff0000, v79
	v_pk_mul_f32 v[112:113], v[4:5], v[112:113] op_sel_hi:[0,1]
	v_pk_mul_f32 v[114:115], v[4:5], v[114:115] op_sel_hi:[0,1]
	v_pk_mul_f32 v[116:117], v[4:5], v[116:117] op_sel_hi:[0,1]
	v_pk_mul_f32 v[118:119], v[4:5], v[118:119] op_sel_hi:[0,1]
	v_pk_mul_f32 v[112:113], v[12:13], v[112:113]
	v_pk_mul_f32 v[114:115], v[14:15], v[114:115]
	v_pk_mul_f32 v[116:117], v[16:17], v[116:117]
	v_pk_mul_f32 v[118:119], v[18:19], v[118:119]
	s_and_saveexec_b64 s[28:29], s[20:21]
	global_store_dwordx4 v[90:91], v[104:107], off nt
	global_store_dwordx4 v[90:91], v[108:111], off offset:16 nt
	s_mov_b64 exec, s[28:29]
	s_and_saveexec_b64 s[28:29], s[22:23]
	global_store_dwordx4 v[92:93], v[112:115], off nt
	global_store_dwordx4 v[92:93], v[116:119], off offset:16 nt
	s_mov_b64 exec, s[28:29]
	s_andn2_b64 exec, exec, s[12:13]
	s_cbranch_execnz .Lfin_loop
